# start stagger skipped for the 64 workgroups that own an extra GEMM unit in phases 2/6/10/14
# speedup vs baseline: 1.0212x; 1.0022x over previous
.LBB0_96:
	s_lshl_b32 s2, 1, s55
	s_and_b32 s2, s2, 0x4444
	s_cbranch_scc0 .Lstg_skip
	s_lshr_b32 s2, s54, 3
	s_and_b32 s2, s2, 7
	s_cmp_lt_u32 s54, 64
	s_cselect_b32 s2, 0, s2
